# dec-attention K/V tile prefetch block: LDS-DMA M0 from 4 per-item SGPR bases, one 32-bit + one 64-bit address add per piece (on top of v125)
# baseline (speedup 1.0000x reference)
.LBB0_612:
	s_andn2_b64 vcc, exec, s[0:1]
	s_cbranch_vccnz .LBB0_483
	v_mov_b32_e32 v25, v200
	v_cmp_lt_i32_e32 vcc, v204, v206
	v_and_b32_e32 v30, 63, v25
	v_lshlrev_b32_e32 v0, 2, v30
	global_load_dword v31, v0, s[90:91]
	global_load_dword v32, v0, s[90:91] offset:256
	global_load_dword v33, v0, s[90:91] offset:512
	global_load_dword v34, v0, s[90:91] offset:768
	v_cndmask_b32_e32 v8, v205, v204, vcc
	v_cmp_lt_i32_e32 vcc, v202, v206
	v_lshl_add_u32 v4, s30, 1, v159
	v_xor_b32_e32 v7, 32, v205
	v_cndmask_b32_e32 v9, v205, v202, vcc
	v_cmp_lt_i32_e32 vcc, v203, v206
	v_ashrrev_i32_e32 v6, 6, v4
	v_mov_b64_e32 v[2:3], s[42:43]
	v_cndmask_b32_e32 v0, v205, v203, vcc
	v_cmp_lt_i32_e32 vcc, v7, v206
	v_lshlrev_b32_e32 v36, 2, v9
	v_lshlrev_b32_e32 v37, 2, v0
	v_lshlrev_b32_e32 v0, 6, v4
	v_lshl_add_u32 v9, v6, 10, v253
	v_cndmask_b32_e32 v7, v205, v7, vcc
	v_lshlrev_b32_e32 v35, 2, v8
	v_bfe_u32 v38, v25, 6, 2
	v_and_b32_e32 v8, 0x3c0, v0
	v_mad_i64_i32 v[10:11], s[0:1], v9, s72, v[2:3]
	v_and_b32_e32 v39, 15, v25
	v_lshlrev_b32_e32 v40, 2, v7
	v_ashrrev_i32_e32 v7, 31, v6
	v_lshl_or_b32 v12, v38, 4, v8
	v_readlane_b32 s0, v254, 7
	v_bfe_u32 v123, v4, 4, 2
	v_lshlrev_b32_e32 v41, 3, v6
	v_lshlrev_b64 v[6:7], 20, v[6:7]
	v_or3_b32 v116, v12, v9, v39
	v_readlane_b32 s1, v254, 8
	v_or3_b32 v8, v41, s47, v123
	v_ashrrev_i32_e32 v9, 31, v8
	v_lshl_add_u64 v[6:7], s[0:1], 0, v[6:7]
	v_mad_i64_i32 v[118:119], s[0:1], v116, s72, v[2:3]
	v_readlane_b32 s0, v254, 3
	v_lshlrev_b32_e32 v0, 8, v123
	v_lshlrev_b64 v[2:3], 16, v[8:9]
	v_readlane_b32 s1, v254, 4
	v_mov_b32_e32 v5, v1
	v_bfe_u32 v131, v25, 4, 2
	v_and_b32_e32 v4, 48, v25
	v_lshlrev_b32_e32 v13, 2, v38
	v_or_b32_e32 v43, 4, v38
	v_lshl_add_u64 v[8:9], v[118:119], 0, v[0:1]
	v_lshl_add_u64 v[22:23], s[0:1], 0, v[2:3]
	v_readlane_b32 s0, v254, 5
	v_lshl_add_u64 v[20:21], v[10:11], 0, v[0:1]
	v_or_b32_e32 v149, v13, v131
	v_lshlrev_b32_e32 v10, 2, v43
	v_readlane_b32 s1, v254, 6
	v_lshlrev_b32_e32 v0, 18, v123
	v_lshl_add_u64 v[4:5], v[8:9], 0, v[4:5]
	v_bitop3_b32 v44, v13, v39, v131 bitop3:0x36
	v_or_b32_e32 v150, v10, v131
	v_bitop3_b32 v10, v10, v25, v131 bitop3:0x36
	v_lshl_add_u64 v[2:3], s[0:1], 0, v[2:3]
	v_lshl_add_u64 v[120:121], v[6:7], 0, v[0:1]
	v_lshlrev_b32_e32 v0, 8, v149
	s_mov_b64 s[0:1], 0x1000
	v_add_co_u32_e32 v12, vcc, s87, v4
	v_mov_b32_e32 v28, v200
	v_lshlrev_b32_e32 v10, 3, v10
	v_lshl_add_u64 v[16:17], v[4:5], 0, s[0:1]
	v_addc_co_u32_e32 v13, vcc, 0, v5, vcc
	v_lshl_add_u64 v[26:27], v[22:23], 0, v[0:1]
	v_lshlrev_b32_e32 v0, 4, v44
	v_and_b32_e32 v24, 0x78, v10
	global_load_dwordx4 v[4:7], v[16:17], off offset:64
	global_load_dwordx4 v[8:11], v[16:17], off offset:128
	s_nop 0
	global_load_dwordx4 v[12:15], v[12:13], off
	s_nop 0
	global_load_dwordx4 v[16:19], v[16:17], off offset:192
	v_lshl_add_u64 v[26:27], v[26:27], 0, v[0:1]
	v_lshlrev_b32_e32 v0, 8, v150
	v_lshlrev_b32_e32 v45, 8, v28
	v_lshl_add_u64 v[28:29], v[22:23], 0, v[0:1]
	v_and_b32_e32 v45, 0xffff0000, v45
	v_add_u32_e32 v152, 16, v45
	s_waitcnt vmcnt(0)
	v_mul_f32_e32 v0, v31, v32
	ds_bpermute_b32 v46, v40, v0
	v_lshlrev_b32_e32 v148, 10, v38
	v_lshl_add_u32 v153, v30, 4, v152
	v_lshlrev_b32_e32 v0, 1, v24
	v_lshlrev_b32_e32 v154, 10, v43
	s_waitcnt lgkmcnt(0)
	v_fmac_f32_e32 v46, v31, v32
	v_mul_f32_e32 v32, v33, v34
	ds_bpermute_b32 v40, v40, v32
	v_add_u32_e32 v31, v153, v148
	ds_bpermute_b32 v30, v35, v46
	v_readfirstlane_b32 s0, v31
	s_mov_b32 m0, s0
	s_waitcnt lgkmcnt(1)
	v_fmac_f32_e32 v40, v33, v34
	v_or_b32_e32 v34, 8, v38
	global_load_lds_dwordx4 v[26:27], off
	v_lshl_add_u64 v[26:27], v[28:29], 0, v[0:1]
	v_add_u32_e32 v29, v153, v154
	v_lshlrev_b32_e32 v28, 2, v34
	v_readfirstlane_b32 s0, v29
	v_or_b32_e32 v155, v28, v131
	s_mov_b32 m0, s0
	v_lshlrev_b32_e32 v0, 8, v155
	global_load_lds_dwordx4 v[26:27], off
	v_lshl_add_u64 v[26:27], v[22:23], 0, v[0:1]
	v_bitop3_b32 v0, v28, v25, v131 bitop3:0x36
	v_lshlrev_b32_e32 v0, 3, v0
	v_lshlrev_b32_e32 v156, 10, v34
	v_and_b32_e32 v28, 0x78, v0
	v_add_u32_e32 v45, v153, v156
	v_lshlrev_b32_e32 v0, 1, v28
	v_readfirstlane_b32 s0, v45
	v_lshl_add_u64 v[26:27], v[26:27], 0, v[0:1]
	s_mov_b32 m0, s0
	v_bfe_u32 v42, v25, 3, 3
	global_load_lds_dwordx4 v[26:27], off
	v_or_b32_e32 v27, 12, v38
	v_lshlrev_b32_e32 v26, 2, v27
	v_or_b32_e32 v157, v26, v131
	v_lshlrev_b32_e32 v0, 8, v157
	v_lshl_add_u64 v[22:23], v[22:23], 0, v[0:1]
	v_bitop3_b32 v0, v26, v25, v131 bitop3:0x36
	v_lshlrev_b32_e32 v0, 3, v0
	v_lshlrev_b32_e32 v158, 10, v27
	s_waitcnt lgkmcnt(0)
	v_add_f32_e32 v30, v46, v30
	v_and_b32_e32 v26, 0x78, v0
	v_add_u32_e32 v46, v153, v158
	ds_bpermute_b32 v32, v36, v30
	v_lshlrev_b32_e32 v0, 1, v26
	v_readfirstlane_b32 s0, v46
	v_lshl_or_b32 v162, v38, 3, v42
	v_lshl_add_u64 v[22:23], v[22:23], 0, v[0:1]
	s_mov_b32 m0, s0
	v_lshlrev_b32_e32 v0, 9, v162
	global_load_lds_dwordx4 v[22:23], off
	v_lshl_add_u64 v[22:23], v[2:3], 0, v[0:1]
	v_lshrrev_b32_e32 v0, 1, v162
	v_xor_b32_e32 v0, v0, v25
	v_lshlrev_b32_e32 v0, 3, v0
	ds_bpermute_b32 v33, v35, v40
	s_waitcnt lgkmcnt(0)
	v_add_f32_e32 v35, v30, v32
	v_and_b32_e32 v30, 56, v0
	v_lshlrev_b32_e32 v0, 1, v30
	v_lshl_add_u64 v[22:23], v[22:23], 0, v[0:1]
	v_add_u32_e32 v0, 0x4000, v31
	v_lshl_or_b32 v164, v43, 3, v42
	v_readfirstlane_b32 s0, v0
	s_mov_b32 m0, s0
	v_lshlrev_b32_e32 v0, 9, v164
	global_load_lds_dwordx4 v[22:23], off
	v_lshl_add_u64 v[22:23], v[2:3], 0, v[0:1]
	v_lshrrev_b32_e32 v0, 1, v164
	v_xor_b32_e32 v0, v0, v25
	v_lshlrev_b32_e32 v0, 3, v0
	v_and_b32_e32 v32, 56, v0
	v_lshlrev_b32_e32 v0, 1, v32
	v_lshl_add_u64 v[22:23], v[22:23], 0, v[0:1]
	v_add_u32_e32 v0, 0x4000, v29
	v_lshl_or_b32 v165, v34, 3, v42
	v_readfirstlane_b32 s0, v0
	s_mov_b32 m0, s0
	v_lshlrev_b32_e32 v0, 9, v165
	global_load_lds_dwordx4 v[22:23], off
	v_lshl_add_u64 v[22:23], v[2:3], 0, v[0:1]
	v_lshrrev_b32_e32 v0, 1, v165
	v_xor_b32_e32 v0, v0, v25
	v_lshlrev_b32_e32 v0, 3, v0
	v_and_b32_e32 v34, 56, v0
	v_lshlrev_b32_e32 v0, 1, v34
	v_lshl_add_u64 v[22:23], v[22:23], 0, v[0:1]
	v_add_u32_e32 v0, 0x4000, v45
	v_lshl_or_b32 v166, v27, 3, v42
	v_readfirstlane_b32 s0, v0
	v_lshlrev_b32_e32 v0, 9, v166
	v_lshl_add_u64 v[2:3], v[2:3], 0, v[0:1]
	v_lshrrev_b32_e32 v0, 1, v166
	v_xor_b32_e32 v0, v0, v25
	s_mov_b32 m0, s0
	v_lshlrev_b32_e32 v0, 3, v0
	global_load_lds_dwordx4 v[22:23], off
	v_and_b32_e32 v22, 56, v0
	v_lshlrev_b32_e32 v0, 1, v22
	v_lshl_add_u64 v[2:3], v[2:3], 0, v[0:1]
	v_add_u32_e32 v0, 0x4000, v46
	v_cmp_lt_i32_e32 vcc, v218, v206
	v_readfirstlane_b32 s0, v0
	s_mov_b32 m0, s0
	ds_bpermute_b32 v0, v37, v35
	global_load_lds_dwordx4 v[2:3], off
	v_add_f32_e32 v2, v40, v33
	ds_bpermute_b32 v3, v36, v2
	s_waitcnt lgkmcnt(0)
	v_add_f32_e32 v159, v35, v0
	s_mov_b64 s[0:1], 0x1400
	v_lshl_add_u64 v[124:125], v[20:21], 0, s[0:1]
	v_readlane_b32 s0, v255, 8
	v_add_f32_e32 v0, v2, v3
	ds_bpermute_b32 v2, v37, v0
	v_cndmask_b32_e32 v3, v205, v218, vcc
	v_lshlrev_b32_e32 v3, 2, v3
	ds_bpermute_b32 v163, v3, v159
	v_bitop3_b32 v21, v131, v25, 15 bitop3:0x78
	s_waitcnt lgkmcnt(0)
	v_add_f32_e32 v160, v0, v2
	ds_bpermute_b32 v161, v3, v160
	v_lshrrev_b32_e32 v0, 1, v25
	v_bfe_u32 v3, v25, 5, 1
	v_bfe_u32 v2, v25, 1, 3
	v_and_b32_e32 v169, 8, v0
	v_bitop3_b32 v0, v3, v0, 7 bitop3:0x78
	v_lshlrev_b32_e32 v174, 4, v0
	v_bitop3_b32 v0, v3, v2, 2 bitop3:0x36
	v_lshlrev_b32_e32 v175, 4, v0
	v_bitop3_b32 v0, v3, v2, 4 bitop3:0x36
	v_lshlrev_b32_e32 v176, 4, v0
	v_bitop3_b32 v0, v3, v2, 6 bitop3:0x36
	v_add3_u32 v2, s47, v41, v123
	v_ashrrev_i32_e32 v3, 31, v2
	v_lshlrev_b64 v[2:3], 16, v[2:3]
	v_readlane_b32 s1, v255, 9
	v_lshlrev_b32_e32 v170, 4, v21
	v_bitop3_b32 v21, v131, v39, 4 bitop3:0x36
	v_lshl_add_u64 v[126:127], s[0:1], 0, v[2:3]
	v_readlane_b32 s0, v255, 10
	v_lshlrev_b32_e32 v171, 4, v21
	v_bitop3_b32 v21, v131, v39, 8 bitop3:0x36
	v_readlane_b32 s1, v255, 11
	v_lshlrev_b32_e32 v20, 3, v44
	v_lshlrev_b32_e32 v172, 4, v21
	v_bitop3_b32 v21, v131, v39, 12 bitop3:0x36
	v_lshl_add_u64 v[128:129], s[0:1], 0, v[2:3]
	v_mov_b32_e32 v2, v1
	v_mov_b32_e32 v3, v1
	v_lshlrev_b32_e32 v167, 8, v39
	v_lshlrev_b32_e32 v168, 7, v39
	v_lshlrev_b32_e32 v173, 4, v21
	v_lshlrev_b32_e32 v177, 4, v0
	v_mov_b32_e32 v0, v1
	v_lshlrev_b32_e32 v132, 1, v20
	v_lshlrev_b32_e32 v134, 1, v24
	v_lshlrev_b32_e32 v136, 1, v28
	v_lshlrev_b32_e32 v138, 1, v26
	v_lshlrev_b32_e32 v140, 1, v30
	v_lshlrev_b32_e32 v142, 1, v32
	v_lshlrev_b32_e32 v144, 1, v34
	v_lshlrev_b32_e32 v146, 1, v22
	v_mov_b64_e32 v[30:31], v[2:3]
	v_mov_b64_e32 v[22:23], v[2:3]
	v_mov_b64_e32 v[38:39], v[2:3]
	v_mov_b64_e32 v[46:47], v[2:3]
	v_mov_b64_e32 v[54:55], v[2:3]
	v_mov_b64_e32 v[62:63], v[2:3]
	v_mov_b64_e32 v[70:71], v[2:3]
	v_mov_b64_e32 v[78:79], v[2:3]
	v_mov_b64_e32 v[26:27], v[2:3]
	v_mov_b64_e32 v[34:35], v[2:3]
	v_mov_b64_e32 v[42:43], v[2:3]
	v_mov_b64_e32 v[50:51], v[2:3]
	v_mov_b64_e32 v[58:59], v[2:3]
	v_mov_b64_e32 v[66:67], v[2:3]
	v_mov_b64_e32 v[74:75], v[2:3]
	v_mov_b64_e32 v[82:83], v[2:3]
	s_mov_b32 s30, 0
	v_ashrrev_i32_e32 v117, 31, v116
	v_lshlrev_b32_e32 v122, 7, v123
	v_mov_b32_e32 v100, 0xff800000
	v_mov_b32_e32 v178, 0
	s_movk_i32 s84, 0xff40
	v_mov_b64_e32 v[28:29], v[0:1]
	v_mov_b64_e32 v[20:21], v[0:1]
	v_mov_b64_e32 v[36:37], v[0:1]
	v_mov_b64_e32 v[44:45], v[0:1]
	v_mov_b64_e32 v[52:53], v[0:1]
	v_mov_b64_e32 v[60:61], v[0:1]
	v_mov_b64_e32 v[68:69], v[0:1]
	v_mov_b64_e32 v[76:77], v[0:1]
	v_mov_b64_e32 v[24:25], v[0:1]
	v_mov_b64_e32 v[32:33], v[0:1]
	v_mov_b64_e32 v[40:41], v[0:1]
	v_mov_b64_e32 v[48:49], v[0:1]
	v_mov_b64_e32 v[56:57], v[0:1]
	v_mov_b64_e32 v[64:65], v[0:1]
	v_mov_b64_e32 v[72:73], v[0:1]
	v_mov_b64_e32 v[80:81], v[0:1]
	v_mov_b32_e32 v179, 0
	v_mov_b32_e32 v181, 0xff800000
	s_mov_b32 s31, 0
	v_add_u32_e32 v84, v153, v148
	v_add_u32_e32 v85, v153, v154
	v_add_u32_e32 v86, v153, v156
	v_add_u32_e32 v87, v153, v158
	v_readfirstlane_b32 s98, v84
	v_readfirstlane_b32 s99, v85
	v_readfirstlane_b32 s100, v86
	v_readfirstlane_b32 s101, v87

.LBB0_618:
	s_add_i32 s1, s30, 0x8000
	s_and_b32 s1, s1, 0x8000
	s_lshl_b32 s4, s4, 1
	s_lshl_b32 s0, s0, 1
	s_add_i32 s5, s1, 0x4000
	v_mul_u32_u24_e32 v0, s4, v149
	s_add_i32 m0, s98, s1
	v_add_u32_e32 v0, v0, v132
	v_lshl_add_u64 v[86:87], v[84:85], 0, v[0:1]
	global_load_lds_dwordx4 v[86:87], off
	v_mul_u32_u24_e32 v0, s4, v150
	s_add_i32 m0, s99, s1
	v_add_u32_e32 v0, v0, v134
	v_lshl_add_u64 v[86:87], v[84:85], 0, v[0:1]
	global_load_lds_dwordx4 v[86:87], off
	v_mul_u32_u24_e32 v0, s4, v155
	s_add_i32 m0, s100, s1
	v_add_u32_e32 v0, v0, v136
	v_lshl_add_u64 v[86:87], v[84:85], 0, v[0:1]
	global_load_lds_dwordx4 v[86:87], off
	v_mul_u32_u24_e32 v0, s4, v157
	s_add_i32 m0, s101, s1
	v_add_u32_e32 v0, v0, v138
	v_lshl_add_u64 v[86:87], v[84:85], 0, v[0:1]
	global_load_lds_dwordx4 v[86:87], off
	v_mul_u32_u24_e32 v0, s0, v162
	s_add_i32 m0, s98, s5
	v_add_u32_e32 v0, v0, v140
	v_lshl_add_u64 v[86:87], v[2:3], 0, v[0:1]
	global_load_lds_dwordx4 v[86:87], off
	v_mul_u32_u24_e32 v0, s0, v164
	s_add_i32 m0, s99, s5
	v_add_u32_e32 v0, v0, v142
	v_lshl_add_u64 v[86:87], v[2:3], 0, v[0:1]
	global_load_lds_dwordx4 v[86:87], off
	v_mul_u32_u24_e32 v0, s0, v165
	s_add_i32 m0, s100, s5
	v_add_u32_e32 v0, v0, v144
	v_lshl_add_u64 v[86:87], v[2:3], 0, v[0:1]
	global_load_lds_dwordx4 v[86:87], off
	v_mul_u32_u24_e32 v0, s0, v166
	s_add_i32 m0, s101, s5
	v_add_u32_e32 v0, v0, v146
	v_lshl_add_u64 v[86:87], v[2:3], 0, v[0:1]
	global_load_lds_dwordx4 v[86:87], off
